# attention: waves 4-7 start each prompt tile ~320 cycles later (stagger of SIMD partners)
# baseline (speedup 1.0000x reference)
; __device__ __forceinline__ unsigned pk2(float lo, float hi) { const bfx2 b = __builtin_convertvector((f32x2){lo, hi}, bfx2); return __builtin_bit_cast(unsigned, b); }
; __device__ __forceinline__ void loader_stage(Frame& F, const void* kp, const void* vp, int pitch, bool isf32, int nvalid, int lt, int boff) {
;     const int key = lt >> 2, ch = lt & 3;
; #pragma unroll
;     for (int kv = 0; kv < 2; ++kv) { const void* sp = kv ? vp : kp; u32x2 r[8];
; #pragma unroll
;         for (int j = 0; j < 8; ++j) r[j] = (u32x2){0u, 0u};
;         if (key < nvalid) {
;             if (isf32) { const float* s = (const float*)sp + (size_t)key * pitch + 4 * ch; f32x4 a[8];
; #pragma unroll
;                 for (int j = 0; j < 8; ++j) a[j] = *(const f32x4*)(s + 16 * j);
; #pragma unroll
;                 for (int j = 0; j < 8; ++j) { r[j].x = pk2(a[j].x, a[j].y); r[j].y = pk2(a[j].z, a[j].w); } }
;             else { const bf16* s = (const bf16*)sp + (size_t)key * pitch + 4 * ch;
; #pragma unroll
;                 for (int j = 0; j < 8; ++j) r[j] = *(const u32x2*)(s + 16 * j); } }
; __device__ __forceinline__ void attn_item(const P& p, Frame& F, const bool is_s, const int b, const int g, const int c) {
;     ...
;             int tid = F.tid; asm volatile("" : "+v"(tid));
;             const bool loader = is_s && tid >= 256;
;             const int boff = (is_s || mode == 0) ? (i & 1) * A_BUF2 : 0;
;             if (is_s) {
;                 if (i == 0) { __syncthreads(); if (loader) loader_stage(F, kp, vp, pitch, mode == 1, nvalid, tid - 256, 0); }
;                 __syncthreads();
;                 if (loader && i + 1 < ntiles) { const void* kp1; const void* vp1; int pitch1, nv1; bool f1; SAMPLE_TILE(i + 1, kp1, vp1, pitch1, f1, nv1); loader_stage(F, kp1, vp1, pitch1, f1, nv1, tid - 256, ((i + 1) & 1) * A_BUF2); }
.LBB0_2060:
	s_mov_b64 s[6:7], 0
	s_and_b64 vcc, exec, s[56:57]
	s_cbranch_vccz .Lattn_stag_skip
	v_readfirstlane_b32 s98, v0
	s_nop 3
	s_bitcmp1_b32 s98, 8
	s_cbranch_scc0 .Lattn_stag_skip
	s_sleep 5
.Lattn_stag_skip:
.LBB0_2061:
	s_andn2_b64 vcc, exec, s[6:7]
	s_cbranch_vccnz .LBB0_2102
	s_cmp_lg_u32 s33, 0
	s_cbranch_scc1 .LBB0_2076
	s_waitcnt lgkmcnt(0)
	s_barrier
	s_and_saveexec_b64 s[46:47], s[0:1]
	s_cbranch_execz .LBB0_2075
	v_add_u32_e32 v2, 0xffffff00, v108
	v_lshrrev_b32_e32 v109, 2, v2
	v_and_b32_e32 v110, 3, v108
	v_cmp_gt_u32_e64 s[14:15], s84, v109
	s_waitcnt vmcnt(3)
	v_mad_u64_u32 v[6:7], s[6:7], v109, s62, 0
	v_lshlrev_b32_e32 v111, 2, v110
	v_mov_b32_e32 v4, 0
	s_waitcnt vmcnt(2)
	v_mov_b32_e32 v8, 0
	v_mov_b32_e32 v9, 0
	v_mov_b32_e32 v100, 0
	v_mov_b32_e32 v101, 0
	v_mov_b32_e32 v10, 0
	v_mov_b32_e32 v11, 0
	v_mov_b32_e32 v102, 0
	v_mov_b32_e32 v103, 0
	s_waitcnt vmcnt(0)
	v_mov_b32_e32 v12, 0
	v_mov_b32_e32 v13, 0
	v_mov_b32_e32 v104, 0
	v_mov_b32_e32 v105, 0
	v_mov_b32_e32 v14, 0
	v_mov_b32_e32 v15, 0
	v_mov_b32_e32 v106, 0
	v_mov_b32_e32 v107, 0
	s_and_saveexec_b64 s[70:71], s[14:15]
	s_cbranch_execz .LBB0_2069
	s_mov_b64 s[6:7], -1
	s_and_b64 vcc, exec, s[80:81]
	s_cbranch_vccz .LBB0_2067
	v_lshl_add_u64 v[8:9], v[6:7], 1, v[98:99]
	v_lshlrev_b32_e32 v2, 1, v111
	v_lshl_add_u64 v[106:107], v[8:9], 0, v[2:3]
	global_load_dwordx2 v[8:9], v[106:107], off
	global_load_dwordx2 v[100:101], v[106:107], off offset:32
	global_load_dwordx2 v[10:11], v[106:107], off offset:64
	global_load_dwordx2 v[102:103], v[106:107], off offset:96
	global_load_dwordx2 v[12:13], v[106:107], off offset:128
	global_load_dwordx2 v[104:105], v[106:107], off offset:160
	global_load_dwordx2 v[14:15], v[106:107], off offset:192
	s_nop 0
	global_load_dwordx2 v[106:107], v[106:107], off offset:224
	s_mov_b64 s[6:7], 0

; #define LAS __attribute__((address_space(3)))
; template <int LO, int HI> __global__ void __launch_bounds__(NTHR, 2) mega(P p) {
;     extern __shared__ __attribute__((aligned(16))) unsigned char lds_[];
;     Frame F; F.lds = (LAS unsigned char*)lds_; F.tid = threadIdx.x; F.lane = F.tid & 63; F.wave = __builtin_amdgcn_readfirstlane(F.tid >> 6); F.G = gridDim.x; F.bid = blockIdx.x;
	.amdhsa_kernel _Z4megaILi0ELi17EEv1P
		.amdhsa_group_segment_fixed_size 0
		.amdhsa_private_segment_fixed_size 0
		.amdhsa_kernarg_size 584
		.amdhsa_user_sgpr_count 2
		.amdhsa_user_sgpr_dispatch_ptr 0
		.amdhsa_user_sgpr_queue_ptr 0
		.amdhsa_user_sgpr_kernarg_segment_ptr 1
		.amdhsa_user_sgpr_dispatch_id 0
		.amdhsa_user_sgpr_kernarg_preload_length 0
		.amdhsa_user_sgpr_kernarg_preload_offset 0
		.amdhsa_user_sgpr_private_segment_size 0
		.amdhsa_uses_dynamic_stack 0
		.amdhsa_enable_private_segment 0
		.amdhsa_system_sgpr_workgroup_id_x 1
		.amdhsa_system_sgpr_workgroup_id_y 0
		.amdhsa_system_sgpr_workgroup_id_z 0
		.amdhsa_system_sgpr_workgroup_info 0
		.amdhsa_system_vgpr_workitem_id 0
		.amdhsa_next_free_vgpr 255
		.amdhsa_next_free_sgpr 102
		.amdhsa_accum_offset 256
		.amdhsa_reserve_vcc 1
		.amdhsa_float_round_mode_32 0
		.amdhsa_float_round_mode_16_64 0
		.amdhsa_float_denorm_mode_32 3
		.amdhsa_float_denorm_mode_16_64 3
		.amdhsa_dx10_clamp 1
		.amdhsa_ieee_mode 1
		.amdhsa_fp16_overflow 0
		.amdhsa_tg_split 0
		.amdhsa_exception_fp_ieee_invalid_op 0
		.amdhsa_exception_fp_denorm_src 0
		.amdhsa_exception_fp_ieee_div_zero 0
		.amdhsa_exception_fp_ieee_overflow 0
		.amdhsa_exception_fp_ieee_underflow 0
		.amdhsa_exception_fp_ieee_inexact 0
		.amdhsa_exception_int_div_zero 0
	.end_amdhsa_kernel

; #define LAS __attribute__((address_space(3)))
; template <int LO, int HI> __global__ void __launch_bounds__(NTHR, 2) mega(P p) {
;     extern __shared__ __attribute__((aligned(16))) unsigned char lds_[];
;     Frame F; F.lds = (LAS unsigned char*)lds_; F.tid = threadIdx.x; F.lane = F.tid & 63; F.wave = __builtin_amdgcn_readfirstlane(F.tid >> 6); F.G = gridDim.x; F.bid = blockIdx.x;
amdhsa.kernels:
  - .agpr_count:     0
    .args:
      - .offset:         0
        .size:           328
        .value_kind:     by_value
      - .offset:         328
        .size:           4
        .value_kind:     hidden_block_count_x
      - .offset:         332
        .size:           4
        .value_kind:     hidden_block_count_y
      - .offset:         336
        .size:           4
        .value_kind:     hidden_block_count_z
      - .offset:         340
        .size:           2
        .value_kind:     hidden_group_size_x
      - .offset:         342
        .size:           2
        .value_kind:     hidden_group_size_y
      - .offset:         344
        .size:           2
        .value_kind:     hidden_group_size_z
      - .offset:         346
        .size:           2
        .value_kind:     hidden_remainder_x
      - .offset:         348
        .size:           2
        .value_kind:     hidden_remainder_y
      - .offset:         350
        .size:           2
        .value_kind:     hidden_remainder_z
      - .offset:         368
        .size:           8
        .value_kind:     hidden_global_offset_x
      - .offset:         376
        .size:           8
        .value_kind:     hidden_global_offset_y
      - .offset:         384
        .size:           8
        .value_kind:     hidden_global_offset_z
      - .offset:         392
        .size:           2
        .value_kind:     hidden_grid_dims
      - .offset:         448
        .size:           4
        .value_kind:     hidden_dynamic_lds_size
    .group_segment_fixed_size: 0
    .kernarg_segment_align: 8
    .kernarg_segment_size: 584
    .language:       OpenCL C
    .language_version:
      - 2
      - 0
    .max_flat_workgroup_size: 512
    .name:           _Z4megaILi0ELi17EEv1P
    .private_segment_fixed_size: 0
    .sgpr_count:     108
    .sgpr_spill_count: 205
    .symbol:         _Z4megaILi0ELi17EEv1P.kd
    .uniform_work_group_size: 1
    .uses_dynamic_stack: false
    .vgpr_count:     255
    .vgpr_spill_count: 0
    .wavefront_size: 64
